# A item epilogue: the 8 sub-RMSNorm gain loads and 4 gate loads issued together before the rsqrt chain (one wait instead of 8 waits that also drained the previous stores)
# speedup vs baseline: 1.0156x; 1.0010x over previous
.LBB0_389:
	s_or_b64 exec, exec, s[2:3]
	v_lshlrev_b32_e32 v1, 5, v159
	v_ashrrev_i32_e32 v28, 2, v159
	s_movk_i32 s2, 0x210
	v_and_b32_e32 v44, 0x60, v1
	v_mul_lo_u32 v0, v28, s2
	v_lshlrev_b32_e32 v184, 2, v44
	v_add3_u32 v4, 0, v0, v184
	s_waitcnt lgkmcnt(0)
	s_barrier
	ds_read_b128 v[32:35], v4
	ds_read_b128 v[24:27], v4 offset:16
	ds_read_b128 v[20:23], v4 offset:32
	ds_read_b128 v[16:19], v4 offset:48
	ds_read_b128 v[12:15], v4 offset:64
	ds_read_b128 v[8:11], v4 offset:80
	s_waitcnt lgkmcnt(5)
	v_mul_f32_e32 v0, v33, v33
	s_waitcnt lgkmcnt(4)
	v_mul_f32_e32 v1, v25, v25
	v_fmac_f32_e32 v0, v32, v32
	v_fmac_f32_e32 v1, v24, v24
	v_fmac_f32_e32 v0, v34, v34
	v_fmac_f32_e32 v1, v26, v26
	v_fmac_f32_e32 v0, v35, v35
	v_fmac_f32_e32 v1, v27, v27
	v_add_f32_e32 v0, v0, v1
	s_waitcnt lgkmcnt(3)
	v_mul_f32_e32 v1, v21, v21
	v_fmac_f32_e32 v1, v20, v20
	v_fmac_f32_e32 v1, v22, v22
	v_fmac_f32_e32 v1, v23, v23
	v_add_f32_e32 v0, v0, v1
	s_waitcnt lgkmcnt(2)
	v_mul_f32_e32 v1, v17, v17
	v_fmac_f32_e32 v1, v16, v16
	v_fmac_f32_e32 v1, v18, v18
	v_fmac_f32_e32 v1, v19, v19
	v_add_f32_e32 v0, v0, v1
	s_waitcnt lgkmcnt(1)
	v_mul_f32_e32 v1, v13, v13
	v_fmac_f32_e32 v1, v12, v12
	v_fmac_f32_e32 v1, v14, v14
	v_fmac_f32_e32 v1, v15, v15
	v_add_f32_e32 v0, v0, v1
	s_waitcnt lgkmcnt(0)
	v_mul_f32_e32 v1, v9, v9
	v_fmac_f32_e32 v1, v8, v8
	v_fmac_f32_e32 v1, v10, v10
	v_fmac_f32_e32 v1, v11, v11
	v_add_f32_e32 v29, v0, v1
	ds_read_b128 v[0:3], v4 offset:112
	ds_read_b128 v[4:7], v4 offset:96
	s_ashr_i32 s3, s64, 31
	s_add_u32 s2, s18, s64
	s_addc_u32 s3, s19, s3
	s_waitcnt lgkmcnt(1)
	v_pk_mul_f32 v[40:41], v[0:1], v[0:1]
	s_waitcnt lgkmcnt(0)
	v_pk_mul_f32 v[38:39], v[4:5], v[4:5]
	v_pk_mul_f32 v[30:31], v[6:7], v[6:7]
	v_pk_mul_f32 v[36:37], v[2:3], v[2:3]
	v_mov_b32_e32 v42, v38
	v_mov_b32_e32 v43, v40
	v_mov_b32_e32 v40, v39
	v_pk_add_f32 v[38:39], v[42:43], v[40:41]
	v_mov_b32_e32 v40, v30
	v_mov_b32_e32 v41, v36
	v_pk_add_f32 v[38:39], v[38:39], v[40:41]
	v_mov_b32_e32 v36, v31
	v_pk_add_f32 v[30:31], v[38:39], v[36:37]
	v_lshl_add_u64 v[38:39], s[12:13], 0, v[184:185]
	v_add_f32_e32 v29, v29, v30
	v_add_f32_e32 v29, v29, v31
	ds_swizzle_b32 v30, v29 offset:swizzle(SWAP,1)
	v_lshlrev_b32_e32 v184, 1, v44
	global_load_dwordx4 v[64:67], v[38:39], off
	global_load_dwordx4 v[68:71], v[38:39], off offset:16
	global_load_dwordx4 v[72:75], v[38:39], off offset:32
	global_load_dwordx4 v[76:79], v[38:39], off offset:48
	global_load_dwordx4 v[80:83], v[38:39], off offset:64
	global_load_dwordx4 v[84:87], v[38:39], off offset:80
	global_load_dwordx4 v[88:91], v[38:39], off offset:96
	global_load_dwordx4 v[92:95], v[38:39], off offset:112
	v_mov_b32_e32 v46, v28
	v_ashrrev_i32_e32 v47, 31, v28
	v_lshl_add_u64 v[46:47], s[2:3], 0, v[46:47]
	v_lshlrev_b64 v[46:47], 11, v[46:47]
	v_lshl_add_u64 v[46:47], s[14:15], 0, v[46:47]
	v_lshl_add_u64 v[46:47], v[46:47], 0, s[22:23]
	v_lshl_add_u64 v[36:37], v[46:47], 0, v[184:185]
	global_load_dwordx4 v[96:99], v[36:37], off
	global_load_dwordx4 v[100:103], v[36:37], off offset:16
	global_load_dwordx4 v[104:107], v[36:37], off offset:32
	global_load_dwordx4 v[108:111], v[36:37], off offset:48
	s_waitcnt lgkmcnt(0)
	v_add_f32_e32 v29, v29, v30
	ds_swizzle_b32 v30, v29 offset:swizzle(SWAP,2)
	s_waitcnt lgkmcnt(0)
	v_add_f32_e32 v29, v29, v30
	v_fmamk_f32 v29, v29, 0x3c000000, v227
	v_rsq_f32_e32 v29, v29
	v_sub_f32_e32 v30, 1.0, v158
	v_mul_f32_e32 v40, v30, v29
	v_mul_f32_e32 v32, v32, v40
	v_mul_f32_e32 v33, v33, v40
	v_mul_f32_e32 v34, v34, v40
	v_mul_f32_e32 v35, v35, v40
	v_mul_f32_e32 v24, v24, v40
	v_mul_f32_e32 v25, v25, v40
	v_mul_f32_e32 v26, v26, v40
	v_mul_f32_e32 v27, v27, v40
	v_mul_f32_e32 v20, v20, v40
	v_mul_f32_e32 v21, v21, v40
	v_mul_f32_e32 v22, v22, v40
	v_mul_f32_e32 v23, v23, v40
	v_mul_f32_e32 v16, v16, v40
	v_mul_f32_e32 v17, v17, v40
	v_mul_f32_e32 v18, v18, v40
	v_mul_f32_e32 v19, v19, v40
	v_mul_f32_e32 v12, v12, v40
	v_mul_f32_e32 v13, v13, v40
	v_mul_f32_e32 v14, v14, v40
	v_mul_f32_e32 v15, v15, v40
	v_mul_f32_e32 v8, v8, v40
	v_mul_f32_e32 v9, v9, v40
	v_mul_f32_e32 v10, v10, v40
	v_mul_f32_e32 v11, v11, v40
	v_mul_f32_e32 v4, v4, v40
	v_mul_f32_e32 v5, v5, v40
	v_mul_f32_e32 v6, v6, v40
	v_mul_f32_e32 v7, v7, v40
	v_mul_f32_e32 v0, v0, v40
	v_mul_f32_e32 v1, v1, v40
	v_mul_f32_e32 v2, v2, v40
	v_mul_f32_e32 v3, v3, v40
	s_waitcnt vmcnt(0)
	v_mul_f32_e32 v32, v64, v32
	v_lshlrev_b32_e32 v48, 16, v96
	v_mul_f32_e32 v32, v32, v48
	v_mul_f32_e32 v33, v65, v33
	v_and_b32_e32 v48, 0xffff0000, v96
	v_mul_f32_e32 v33, v33, v48
	v_mul_f32_e32 v34, v66, v34
	v_lshlrev_b32_e32 v48, 16, v97
	v_mul_f32_e32 v34, v34, v48
	v_mul_f32_e32 v35, v67, v35
	v_and_b32_e32 v48, 0xffff0000, v97
	v_mul_f32_e32 v35, v35, v48
	v_mul_f32_e32 v24, v68, v24
	v_lshlrev_b32_e32 v48, 16, v98
	v_mul_f32_e32 v24, v24, v48
	v_mul_f32_e32 v25, v69, v25
	v_and_b32_e32 v48, 0xffff0000, v98
	v_mul_f32_e32 v25, v25, v48
	v_mul_f32_e32 v26, v70, v26
	v_lshlrev_b32_e32 v48, 16, v99
	v_mul_f32_e32 v26, v26, v48
	v_mul_f32_e32 v27, v71, v27
	v_and_b32_e32 v48, 0xffff0000, v99
	v_mul_f32_e32 v27, v27, v48
	v_cvt_pk_bf16_f32 v112, v32, v33
	v_cvt_pk_bf16_f32 v113, v34, v35
	v_cvt_pk_bf16_f32 v114, v24, v25
	v_cvt_pk_bf16_f32 v115, v26, v27
	global_store_dwordx4 v[36:37], v[112:115], off
	v_mul_f32_e32 v20, v72, v20
	v_lshlrev_b32_e32 v48, 16, v100
	v_mul_f32_e32 v20, v20, v48
	v_mul_f32_e32 v21, v73, v21
	v_and_b32_e32 v48, 0xffff0000, v100
	v_mul_f32_e32 v21, v21, v48
	v_mul_f32_e32 v22, v74, v22
	v_lshlrev_b32_e32 v48, 16, v101
	v_mul_f32_e32 v22, v22, v48
	v_mul_f32_e32 v23, v75, v23
	v_and_b32_e32 v48, 0xffff0000, v101
	v_mul_f32_e32 v23, v23, v48
	v_mul_f32_e32 v16, v76, v16
	v_lshlrev_b32_e32 v48, 16, v102
	v_mul_f32_e32 v16, v16, v48
	v_mul_f32_e32 v17, v77, v17
	v_and_b32_e32 v48, 0xffff0000, v102
	v_mul_f32_e32 v17, v17, v48
	v_mul_f32_e32 v18, v78, v18
	v_lshlrev_b32_e32 v48, 16, v103
	v_mul_f32_e32 v18, v18, v48
	v_mul_f32_e32 v19, v79, v19
	v_and_b32_e32 v48, 0xffff0000, v103
	v_mul_f32_e32 v19, v19, v48
	v_cvt_pk_bf16_f32 v116, v20, v21
	v_cvt_pk_bf16_f32 v117, v22, v23
	v_cvt_pk_bf16_f32 v118, v16, v17
	v_cvt_pk_bf16_f32 v119, v18, v19
	global_store_dwordx4 v[36:37], v[116:119], off offset:16
	v_mul_f32_e32 v12, v80, v12
	v_lshlrev_b32_e32 v48, 16, v104
	v_mul_f32_e32 v12, v12, v48
	v_mul_f32_e32 v13, v81, v13
	v_and_b32_e32 v48, 0xffff0000, v104
	v_mul_f32_e32 v13, v13, v48
	v_mul_f32_e32 v14, v82, v14
	v_lshlrev_b32_e32 v48, 16, v105
	v_mul_f32_e32 v14, v14, v48
	v_mul_f32_e32 v15, v83, v15
	v_and_b32_e32 v48, 0xffff0000, v105
	v_mul_f32_e32 v15, v15, v48
	v_mul_f32_e32 v8, v84, v8
	v_lshlrev_b32_e32 v48, 16, v106
	v_mul_f32_e32 v8, v8, v48
	v_mul_f32_e32 v9, v85, v9
	v_and_b32_e32 v48, 0xffff0000, v106
	v_mul_f32_e32 v9, v9, v48
	v_mul_f32_e32 v10, v86, v10
	v_lshlrev_b32_e32 v48, 16, v107
	v_mul_f32_e32 v10, v10, v48
	v_mul_f32_e32 v11, v87, v11
	v_and_b32_e32 v48, 0xffff0000, v107
	v_mul_f32_e32 v11, v11, v48
	v_cvt_pk_bf16_f32 v120, v12, v13
	v_cvt_pk_bf16_f32 v121, v14, v15
	v_cvt_pk_bf16_f32 v122, v8, v9
	v_cvt_pk_bf16_f32 v123, v10, v11
	global_store_dwordx4 v[36:37], v[120:123], off offset:32
	v_mul_f32_e32 v4, v88, v4
	v_lshlrev_b32_e32 v48, 16, v108
	v_mul_f32_e32 v4, v4, v48
	v_mul_f32_e32 v5, v89, v5
	v_and_b32_e32 v48, 0xffff0000, v108
	v_mul_f32_e32 v5, v5, v48
	v_mul_f32_e32 v6, v90, v6
	v_lshlrev_b32_e32 v48, 16, v109
	v_mul_f32_e32 v6, v6, v48
	v_mul_f32_e32 v7, v91, v7
	v_and_b32_e32 v48, 0xffff0000, v109
	v_mul_f32_e32 v7, v7, v48
	v_mul_f32_e32 v0, v92, v0
	v_lshlrev_b32_e32 v48, 16, v110
	v_mul_f32_e32 v0, v0, v48
	v_mul_f32_e32 v1, v93, v1
	v_and_b32_e32 v48, 0xffff0000, v110
	v_mul_f32_e32 v1, v1, v48
	v_mul_f32_e32 v2, v94, v2
	v_lshlrev_b32_e32 v48, 16, v111
	v_mul_f32_e32 v2, v2, v48
	v_mul_f32_e32 v3, v95, v3
	v_and_b32_e32 v48, 0xffff0000, v111
	v_mul_f32_e32 v3, v3, v48
	v_cvt_pk_bf16_f32 v124, v4, v5
	v_cvt_pk_bf16_f32 v125, v6, v7
	v_cvt_pk_bf16_f32 v126, v0, v1
	v_cvt_pk_bf16_f32 v127, v2, v3
	global_store_dwordx4 v[36:37], v[124:127], off offset:48
	s_mov_b64 s[2:3], 0
	s_waitcnt lgkmcnt(0)
	s_barrier
